# nt (non-temporal) on the phase-0 transposed-weight output store, on top of v42
# speedup vs baseline: 1.0021x; 1.0021x over previous
.Ltr_mvdone:
	v_cndmask_b32_e64 v96, 0, v96, s[10:11]
	v_cndmask_b32_e64 v97, 0, v97, s[10:11]
	v_cndmask_b32_e64 v98, 0, v98, s[10:11]
	v_cndmask_b32_e64 v99, 0, v99, s[10:11]
	v_cndmask_b32_e64 v100, 0, v100, s[10:11]
	v_cndmask_b32_e64 v101, 0, v101, s[10:11]
	v_cndmask_b32_e64 v102, 0, v102, s[10:11]
	v_cndmask_b32_e64 v103, 0, v103, s[10:11]
	v_mul_u32_u24_e32 v106, 0x110, v41
	v_add3_u32 v106, v106, v42, s101
	ds_write_b128 v106, v[96:99]
	ds_write_b128 v106, v[100:103] offset:8704
	v_lshlrev_b32_e32 v47, 3, v40
	v_and_b32_e32 v47, 56, v47
	v_mul_u32_u24_e32 v107, 0x110, v47
	v_lshlrev_b32_e32 v48, 2, v44
	v_add3_u32 v107, v107, v48, s101
	v_add_u32_e32 v108, 0x400, v107
	s_waitcnt lgkmcnt(0)
	s_barrier
	ds_read2_b32 v[110:111], v107 offset1:68
	ds_read2_b32 v[112:113], v107 offset0:136 offset1:204
	ds_read2_b32 v[114:115], v108 offset0:16 offset1:84
	ds_read2_b32 v[116:117], v108 offset0:152 offset1:220
	s_xor_b32 s101, s101, 0x4400
	s_add_i32 s99, s99, 1
	s_cmp_ge_u32 s99, 3
	s_cselect_b32 s99, 0, s99
	s_min_u32 s98, s98, 1
	s_add_i32 s98, s98, 1
	s_waitcnt lgkmcnt(3)
	v_cvt_pk_bf16_f32 v118, v110, v111
	s_waitcnt lgkmcnt(2)
	v_cvt_pk_bf16_f32 v119, v112, v113
	s_waitcnt lgkmcnt(1)
	v_cvt_pk_bf16_f32 v120, v114, v115
	s_waitcnt lgkmcnt(0)
	v_cvt_pk_bf16_f32 v121, v116, v117
	global_store_dwordx4 v[104:105], v[118:121], off nt
